# diff attention: causal mask folded into a padded bias LUT (-inf for d<0, clamp by padding), 16 ds_read2_b32 replace 96 VALU + 32 ds_read_b32, mask block removed
# baseline (speedup 1.0000x reference)
; DI int tid() { int t = threadIdx.x; asm volatile("" : "+v"(t)); return t; }
; DI void diff_unit(const Params& p, const int t, int l, int h, int qb, char* lds) {
;   float* lut = (float*)(lds + LUT_OFF);
;   const int lane = t & 63, w = t >> 6, r = lane & 31, hf = lane >> 5, wr = w & 3, map = w >> 2;
;   __syncthreads();
;   if (t < 132) lut[t] = p.BLUT[h * 132 + (t > 128 ? 128 : t)];
;   const float b31 = p.BLUT[h * 132 + 128];
; DI void phase_attn(const Params& p, int l, char* lds) {
;     ...
;     const int u = *ubox;
;     if (u < 0) break;
;     const int h = u / 96, i = u - h * 96;
;     const int t = tid();
;     if (i < 11) mla_unit(p, t, l, h, 31 - i, lds);
;     else {
;       const int k = i - 11, grp = k >> 2, pos = k & 3;
;       if (grp < 21 && pos == 3) mla_unit(p, t, l, h, 20 - grp, lds);
;       else diff_unit(p, t, l, h, 63 - (grp * 3 + pos), lds);
.LBB0_226:
	s_or_b64 exec, exec, s[0:1]
	s_waitcnt lgkmcnt(0)
	s_barrier
	ds_read_b32 v0, v224
	s_waitcnt lgkmcnt(0)
	v_cmp_gt_i32_e32 vcc, 0, v0
	v_readfirstlane_b32 s0, v0
	s_cbranch_vccnz .LBB0_245
	s_mul_hi_u32 s1, s0, 0xaaaaaaab
	s_lshr_b32 s62, s1, 6
	s_mul_i32 s63, s62, 0xffffffa0
	s_add_i32 s63, s63, s0
	v_mov_b32_e32 v233, v222
	s_cmp_gt_i32 s63, 10
	s_mov_b64 s[0:1], -1
	s_cbranch_scc0 .LBB0_266
	s_add_i32 s0, s63, -11
	s_lshr_b32 s2, s0, 2
	s_and_b32 s90, s0, 3
	s_cmpk_gt_u32 s0, 0x53
	s_cselect_b64 s[0:1], -1, 0
	s_cmp_lg_u32 s90, 3
	s_cselect_b64 s[88:89], -1, 0
	s_or_b64 s[88:89], s[0:1], s[88:89]
	s_mov_b64 s[0:1], -1
	s_and_b64 vcc, exec, s[88:89]
	s_cbranch_vccz .LBB0_252
	s_movk_i32 s0, 0x13c
	v_cmp_gt_i32_e32 vcc, s0, v233
	s_mul_i32 s4, s62, 0x84
	s_barrier
	s_and_saveexec_b64 s[0:1], vcc
	s_cbranch_execz .LBB0_231
	v_add_u32_e32 v0, 0xffffffa2, v233
	v_med3_i32 v2, v0, 0, v229
	v_add_u32_e32 v2, s4, v2
	v_readlane_b32 s64, v241, 1
	v_ashrrev_i32_e32 v3, 31, v2
	v_readlane_b32 s68, v241, 5
	v_readlane_b32 s69, v241, 6
	v_readlane_b32 s65, v241, 2
	v_readlane_b32 s66, v241, 3
	v_lshl_add_u64 v[2:3], v[2:3], 2, s[68:69]
	global_load_dword v4, v[2:3], off
	v_lshlrev_b32_e32 v2, 2, v233
	v_add_u32_e32 v2, 0x16000, v2
	v_cmp_gt_i32_e32 vcc, 0, v0
	v_readlane_b32 s67, v241, 4
	v_readlane_b32 s70, v241, 7
	v_readlane_b32 s71, v241, 8
	s_waitcnt vmcnt(0)
	v_cndmask_b32_e32 v0, v4, v230, vcc
	ds_write_b32 v2, v0

; #define MFMA32(a, b, c) __builtin_amdgcn_mfma_f32_32x32x16_bf16((a), (b), (c), 0, 0, 0)
; template <int DQK, int KROW, bool BIAS, bool MAPS2>
; DI void attn_core(const int t, const u16* __restrict__ Q, int ldq, const u16* __restrict__ Kp, int ldk, const u16* __restrict__ Vt, int q0,
;                   char* lds, const float* lut, float b31, f32x16 (&o)[4], float& l_out) {
;     ...
;     const bool live = (kt << 6) <= wq0 + 31;
;     if (live) {
;       const int k0 = kt << 6;
;       const bool far = BIAS && (wq0 - (k0 + 63) >= 128);
;       const float init = (far ? b31 : 0.f) - m_run;
; #pragma unroll
;       for (int k2 = 0; k2 < 2; ++k2)
; #pragma unroll
;         for (int i = 0; i < 16; ++i) s[k2][i] = init;
;       {
;         constexpr int QBS = (NKS > 4) ? 2 : 4, NBT = NKS / QBS;
;         bf16x8 kfb[2][QBS][2];
;         const char* kbase = lds + (kt & 1) * AT_KBUF + r * KS + hf * 16 + map * (DQK * 2);
; #pragma unroll
;         for (int jq = 0; jq < QBS; ++jq)
; #pragma unroll
;           for (int k2 = 0; k2 < 2; ++k2) kfb[0][jq][k2] = *(const bf16x8*)(kbase + 32 * k2 * KS + jq * 32);
; #pragma unroll
;         for (int b = 0; b < NBT; ++b) {
;           if (b + 1 < NBT) {
; #pragma unroll
;             for (int jq = 0; jq < QBS; ++jq)
; #pragma unroll
;               for (int k2 = 0; k2 < 2; ++k2) kfb[(b + 1) & 1][jq][k2] = *(const bf16x8*)(kbase + 32 * k2 * KS + ((b + 1) * QBS + jq) * 32);
;           }
;           __builtin_amdgcn_sched_barrier(0);
;           __builtin_amdgcn_s_setprio(1);
; #pragma unroll
;           for (int jq = 0; jq < QBS; ++jq)
; #pragma unroll
;             for (int k2 = 0; k2 < 2; ++k2) s[k2] = MFMA32(kfb[b & 1][jq][k2], qf[b * QBS + jq], s[k2]);
;           __builtin_amdgcn_s_setprio(0);
;           __builtin_amdgcn_sched_barrier(0);
;         }
;       }
;       if (BIAS && !far) {
; #pragma unroll
;         for (int k2 = 0; k2 < 2; ++k2)
; #pragma unroll
;           for (int i = 0; i < 16; ++i) {
;             const int key = k0 + 32 * k2 + (i & 3) + 8 * (i >> 2) + 4 * hf;
;             int d = qrow - key; d = d < 0 ? 0 : (d > 128 ? 128 : d);
;             s[k2][i] += lut[d];
;           }
;       }
.LBB0_235:
	v_cmp_le_i32_e32 vcc, s90, v155
	s_and_saveexec_b64 s[92:93], vcc
	s_cbranch_execz .LBB0_243
	s_movk_i32 s0, 0x80
	v_cmp_gt_i32_e32 vcc, s0, v159
	s_movk_i32 s0, 0x7f
	v_cmp_lt_i32_e64 s[0:1], s0, v159
	s_and_b32 s91, s96, 1
	s_nop 0
	v_cndmask_b32_e64 v0, 0, v152, s[0:1]
	s_mul_i32 s0, s91, 0x6400
	v_sub_f32_e32 v80, v0, v161
	v_add_u32_e32 v0, s0, v156
	ds_read_b128 v[2:5], v0 offset:8704
	ds_read_b128 v[6:9], v0
	ds_read_b128 v[10:13], v0 offset:32
	ds_read_b128 v[162:165], v0 offset:8736
	ds_read_b128 v[166:169], v0 offset:64
	ds_read_b128 v[170:173], v0 offset:8768
	ds_read_b128 v[174:177], v0 offset:96
	ds_read_b128 v[178:181], v0 offset:8800
	s_setprio 1
	v_mov_b32_e32 v81, v80
	v_mov_b32_e32 v82, v80
	v_mov_b32_e32 v83, v80
	v_mov_b32_e32 v84, v80
	v_mov_b32_e32 v85, v80
	v_mov_b32_e32 v86, v80
	v_mov_b32_e32 v87, v80
	v_mov_b32_e32 v88, v80
	v_mov_b32_e32 v89, v80
	v_mov_b32_e32 v90, v80
	v_mov_b32_e32 v91, v80
	v_mov_b32_e32 v92, v80
	v_mov_b32_e32 v93, v80
	v_mov_b32_e32 v94, v80
	v_mov_b32_e32 v95, v80
	s_waitcnt lgkmcnt(6)
	s_nop 0
	v_mfma_f32_32x32x16_bf16 v[96:111], v[6:9], v[112:115], v[80:95]
	v_mfma_f32_32x32x16_bf16 v[80:95], v[2:5], v[112:115], v[80:95]
	s_waitcnt lgkmcnt(5)
	v_mfma_f32_32x32x16_bf16 v[96:111], v[10:13], v[116:119], v[96:111]
	s_waitcnt lgkmcnt(4)
	v_mfma_f32_32x32x16_bf16 v[80:95], v[162:165], v[116:119], v[80:95]
	s_waitcnt lgkmcnt(3)
	v_mfma_f32_32x32x16_bf16 v[96:111], v[166:169], v[120:123], v[96:111]
	s_waitcnt lgkmcnt(2)
	v_mfma_f32_32x32x16_bf16 v[80:95], v[170:173], v[120:123], v[80:95]
	s_waitcnt lgkmcnt(1)
	v_mfma_f32_32x32x16_bf16 v[96:111], v[174:177], v[124:127], v[96:111]
	s_waitcnt lgkmcnt(0)
	v_mfma_f32_32x32x16_bf16 v[80:95], v[178:181], v[124:127], v[80:95]
	s_setprio 0
	s_and_saveexec_b64 s[0:1], vcc
	s_cbranch_execz .LBB0_238
	v_add_u32_e32 v0, v160, v159
	v_lshlrev_b32_e32 v0, 2, v0
	v_add_u32_e32 v0, 0x16178, v0
	ds_read2_b32 v[2:3], v0 offset0:63 offset1:62
	ds_read2_b32 v[4:5], v0 offset0:61 offset1:60
	ds_read2_b32 v[6:7], v0 offset0:55 offset1:54
	ds_read2_b32 v[8:9], v0 offset0:53 offset1:52
	ds_read2_b32 v[10:11], v0 offset0:47 offset1:46
	ds_read2_b32 v[12:13], v0 offset0:45 offset1:44
	ds_read2_b32 v[14:15], v0 offset0:39 offset1:38
	ds_read2_b32 v[162:163], v0 offset0:37 offset1:36
	ds_read2_b32 v[164:165], v0 offset0:31 offset1:30
	ds_read2_b32 v[166:167], v0 offset0:29 offset1:28
	ds_read2_b32 v[168:169], v0 offset0:23 offset1:22
	ds_read2_b32 v[170:171], v0 offset0:21 offset1:20
	ds_read2_b32 v[172:173], v0 offset0:15 offset1:14
	ds_read2_b32 v[174:175], v0 offset0:13 offset1:12
	ds_read2_b32 v[176:177], v0 offset0:7 offset1:6
	ds_read2_b32 v[178:179], v0 offset0:5 offset1:4
	s_waitcnt lgkmcnt(8)
	v_pk_add_f32 v[108:109], v[108:109], v[14:15]
	v_pk_add_f32 v[110:111], v[110:111], v[162:163]
	v_pk_add_f32 v[106:107], v[106:107], v[12:13]
	v_pk_add_f32 v[104:105], v[104:105], v[10:11]
	v_pk_add_f32 v[102:103], v[102:103], v[8:9]
	v_pk_add_f32 v[100:101], v[100:101], v[6:7]
	v_pk_add_f32 v[98:99], v[98:99], v[4:5]
	v_pk_add_f32 v[96:97], v[96:97], v[2:3]
	s_waitcnt lgkmcnt(0)
	v_pk_add_f32 v[94:95], v[94:95], v[178:179]
	v_pk_add_f32 v[92:93], v[92:93], v[176:177]
	v_pk_add_f32 v[90:91], v[90:91], v[174:175]
	v_pk_add_f32 v[88:89], v[88:89], v[172:173]
	v_pk_add_f32 v[86:87], v[86:87], v[170:171]
	v_pk_add_f32 v[84:85], v[84:85], v[168:169]
	v_pk_add_f32 v[82:83], v[82:83], v[166:167]
	v_pk_add_f32 v[80:81], v[80:81], v[164:165]
; template <int DQK, int KROW, bool BIAS, bool MAPS2>
; DI void attn_core(const int t, const u16* __restrict__ Q, int ldq, const u16* __restrict__ Kp, int ldk, const u16* __restrict__ Vt, int q0,
;                   char* lds, const float* lut, float b31, f32x16 (&o)[4], float& l_out) {
;     ...
;       float mx = s[0][0];
; #pragma unroll
;       for (int k2 = 0; k2 < 2; ++k2)
; #pragma unroll
;         for (int i = 0; i < 16; ++i) mx = fmaxf(mx, s[k2][i]);
;       mx = xhalf_max(mx);
;       if (__builtin_amdgcn_ballot_w64(kt == 0 || mx > RESCALE_THR)) {
;         const float delta = (kt == 0) ? mx : fmaxf(mx, 0.f);
;         const float alpha = __builtin_amdgcn_exp2f(-delta);
;         m_run += delta;
;         l_run *= alpha;
; #pragma unroll
;         for (int dt = 0; dt < 4; ++dt)
; #pragma unroll
;           for (int i = 0; i < 16; ++i) o[dt][i] *= alpha;
; #pragma unroll
;         for (int k2 = 0; k2 < 2; ++k2)
; #pragma unroll
;           for (int i = 0; i < 16; ++i) s[k2][i] -= delta;
;       }
.LBB0_238:
	s_or_b64 exec, exec, s[0:1]
	s_nop 4
	s_nop 0
	v_max_f32_e32 v0, v97, v97
	v_max_f32_e32 v2, v96, v96
	v_max_f32_e32 v0, v2, v0
	v_max3_f32 v0, v0, v98, v99
	v_max3_f32 v0, v0, v100, v101
	v_max3_f32 v0, v0, v102, v103
	v_max3_f32 v0, v0, v104, v105
	v_max3_f32 v0, v0, v106, v107
	v_max3_f32 v0, v0, v108, v109
	v_max3_f32 v0, v0, v110, v111
	v_max3_f32 v0, v0, v80, v81
	v_max3_f32 v0, v0, v82, v83
	v_max3_f32 v0, v0, v84, v85
	v_max3_f32 v0, v0, v86, v87
	v_max3_f32 v0, v0, v88, v89
	v_max3_f32 v0, v0, v90, v91
	v_max3_f32 v0, v0, v92, v93
	v_max3_f32 v0, v0, v94, v95
	v_mov_b32_e32 v2, v0
	s_nop 1
	v_permlane32_swap_b32_e32 v0, v2
	v_max_f32_e32 v2, v2, v2
	v_max_f32_e32 v0, v0, v0
	v_max_f32_e32 v0, v0, v2
	s_cmp_eq_u32 s96, 0
	s_cselect_b64 s[0:1], -1, 0
	v_cmp_lt_f32_e32 vcc, s6, v0
	s_or_b64 vcc, s[0:1], vcc
	s_cbranch_vccz .LBB0_242
	v_max_f32_e32 v2, v0, v0
	v_max_f32_e32 v2, 0, v2
	v_cndmask_b32_e64 v0, v2, v0, s[0:1]
	v_exp_f32_e64 v2, -v0
	v_add_f32_e32 v161, v161, v0
	v_pk_add_f32 v[96:97], v[96:97], v[0:1] op_sel_hi:[1,0] neg_lo:[0,1] neg_hi:[0,1]
	v_pk_add_f32 v[98:99], v[98:99], v[0:1] op_sel_hi:[1,0] neg_lo:[0,1] neg_hi:[0,1]
	v_pk_mul_f32 v[78:79], v[78:79], v[2:3] op_sel_hi:[1,0]
	v_pk_mul_f32 v[76:77], v[76:77], v[2:3] op_sel_hi:[1,0]
	v_pk_mul_f32 v[74:75], v[74:75], v[2:3] op_sel_hi:[1,0]
	v_pk_mul_f32 v[72:73], v[72:73], v[2:3] op_sel_hi:[1,0]
	v_pk_mul_f32 v[70:71], v[70:71], v[2:3] op_sel_hi:[1,0]
	v_pk_mul_f32 v[68:69], v[68:69], v[2:3] op_sel_hi:[1,0]
	v_pk_mul_f32 v[66:67], v[66:67], v[2:3] op_sel_hi:[1,0]
	v_pk_mul_f32 v[64:65], v[64:65], v[2:3] op_sel_hi:[1,0]
	v_pk_mul_f32 v[62:63], v[62:63], v[2:3] op_sel_hi:[1,0]
	v_pk_mul_f32 v[60:61], v[60:61], v[2:3] op_sel_hi:[1,0]
	v_pk_mul_f32 v[58:59], v[58:59], v[2:3] op_sel_hi:[1,0]
	v_pk_mul_f32 v[56:57], v[56:57], v[2:3] op_sel_hi:[1,0]
	v_pk_mul_f32 v[54:55], v[54:55], v[2:3] op_sel_hi:[1,0]
	v_pk_mul_f32 v[52:53], v[52:53], v[2:3] op_sel_hi:[1,0]
	v_pk_mul_f32 v[50:51], v[50:51], v[2:3] op_sel_hi:[1,0]
	v_pk_mul_f32 v[48:49], v[48:49], v[2:3] op_sel_hi:[1,0]
	v_pk_mul_f32 v[46:47], v[46:47], v[2:3] op_sel_hi:[1,0]
	v_pk_mul_f32 v[44:45], v[44:45], v[2:3] op_sel_hi:[1,0]
	v_pk_mul_f32 v[42:43], v[42:43], v[2:3] op_sel_hi:[1,0]
	v_pk_mul_f32 v[40:41], v[40:41], v[2:3] op_sel_hi:[1,0]
	v_pk_mul_f32 v[38:39], v[38:39], v[2:3] op_sel_hi:[1,0]
	v_pk_mul_f32 v[36:37], v[36:37], v[2:3] op_sel_hi:[1,0]
	v_pk_mul_f32 v[34:35], v[34:35], v[2:3] op_sel_hi:[1,0]
	v_pk_mul_f32 v[32:33], v[32:33], v[2:3] op_sel_hi:[1,0]
	v_pk_mul_f32 v[30:31], v[30:31], v[2:3] op_sel_hi:[1,0]
	v_pk_mul_f32 v[28:29], v[28:29], v[2:3] op_sel_hi:[1,0]
	v_pk_mul_f32 v[26:27], v[26:27], v[2:3] op_sel_hi:[1,0]
	v_pk_mul_f32 v[24:25], v[24:25], v[2:3] op_sel_hi:[1,0]
	v_pk_mul_f32 v[22:23], v[22:23], v[2:3] op_sel_hi:[1,0]
	v_pk_mul_f32 v[20:21], v[20:21], v[2:3] op_sel_hi:[1,0]
	v_pk_mul_f32 v[18:19], v[18:19], v[2:3] op_sel_hi:[1,0]
	v_pk_mul_f32 v[16:17], v[16:17], v[2:3] op_sel_hi:[1,0]
	v_pk_add_f32 v[100:101], v[100:101], v[0:1] op_sel_hi:[1,0] neg_lo:[0,1] neg_hi:[0,1]
	v_pk_add_f32 v[102:103], v[102:103], v[0:1] op_sel_hi:[1,0] neg_lo:[0,1] neg_hi:[0,1]
	v_pk_add_f32 v[104:105], v[104:105], v[0:1] op_sel_hi:[1,0] neg_lo:[0,1] neg_hi:[0,1]
	v_pk_add_f32 v[106:107], v[106:107], v[0:1] op_sel_hi:[1,0] neg_lo:[0,1] neg_hi:[0,1]
	v_pk_add_f32 v[108:109], v[108:109], v[0:1] op_sel_hi:[1,0] neg_lo:[0,1] neg_hi:[0,1]
	v_pk_add_f32 v[110:111], v[110:111], v[0:1] op_sel_hi:[1,0] neg_lo:[0,1] neg_hi:[0,1]
	v_pk_add_f32 v[80:81], v[80:81], v[0:1] op_sel_hi:[1,0] neg_lo:[0,1] neg_hi:[0,1]
	v_pk_add_f32 v[82:83], v[82:83], v[0:1] op_sel_hi:[1,0] neg_lo:[0,1] neg_hi:[0,1]
	v_pk_add_f32 v[84:85], v[84:85], v[0:1] op_sel_hi:[1,0] neg_lo:[0,1] neg_hi:[0,1]
	v_pk_add_f32 v[86:87], v[86:87], v[0:1] op_sel_hi:[1,0] neg_lo:[0,1] neg_hi:[0,1]
	v_pk_add_f32 v[88:89], v[88:89], v[0:1] op_sel_hi:[1,0] neg_lo:[0,1] neg_hi:[0,1]
	v_pk_add_f32 v[90:91], v[90:91], v[0:1] op_sel_hi:[1,0] neg_lo:[0,1] neg_hi:[0,1]
	v_pk_add_f32 v[92:93], v[92:93], v[0:1] op_sel_hi:[1,0] neg_lo:[0,1] neg_hi:[0,1]
	v_pk_add_f32 v[94:95], v[94:95], v[0:1] op_sel_hi:[1,0] neg_lo:[0,1] neg_hi:[0,1]
	v_mul_f32_e32 v151, v151, v2
